# prep phase: nt (non-temporal) policy on the 38 once-read 16-byte streaming loads (weights f32, x rows, past latents), on top of stack
# speedup vs baseline: 1.0130x; 1.0112x over previous
.LBB0_31:
	global_load_dwordx4 v[8:11], v[38:39], off offset:-4096 nt
	global_load_dwordx4 v[4:7], v[38:39], off offset:-3072 nt
	global_load_dwordx4 v[12:15], v[38:39], off offset:-2048 nt
	global_load_dwordx4 v[16:19], v[38:39], off nt
	global_load_dwordx4 v[20:23], v[38:39], off offset:-1024 nt
	global_load_dwordx4 v[24:27], v[38:39], off offset:1024 nt
	global_load_dwordx4 v[28:31], v[38:39], off offset:3072 nt
	global_load_dwordx4 v[32:35], v[38:39], off offset:2048 nt
	s_add_i32 s5, s5, s18
	v_lshl_add_u64 v[38:39], v[38:39], 0, s[22:23]
	s_cmpk_lt_i32 s5, 0x100
	s_waitcnt vmcnt(0)
	v_mov_b32_e32 v50, v9
	s_waitcnt vmcnt(6)
	v_mov_b32_e32 v51, v5
	v_mov_b32_e32 v54, v11
	v_mov_b32_e32 v55, v7
	v_mov_b32_e32 v48, v8
	v_mov_b32_e32 v49, v4
	v_mov_b32_e32 v52, v10
	v_mov_b32_e32 v53, v6
	s_waitcnt vmcnt(5)
	v_pk_mul_f32 v[56:57], v[14:15], v[14:15]
	v_pk_mul_f32 v[58:59], v[12:13], v[12:13]
	v_pk_mul_f32 v[50:51], v[50:51], v[50:51]
	v_pk_mul_f32 v[54:55], v[54:55], v[54:55]
	v_pk_mov_b32 v[70:71], v[58:59], v[56:57] op_sel:[1,0]
	v_mov_b32_e32 v59, v57
	v_pk_fma_f32 v[48:49], v[48:49], v[48:49], v[50:51]
	v_pk_fma_f32 v[50:51], v[52:53], v[52:53], v[54:55]
	s_waitcnt vmcnt(3)
	v_mul_f32_e32 v2, v21, v21
	v_mul_f32_e32 v60, v23, v23
	s_waitcnt vmcnt(2)
	v_pk_mul_f32 v[62:63], v[26:27], v[26:27]
	v_pk_mul_f32 v[64:65], v[24:25], v[24:25]
	v_pk_add_f32 v[52:53], v[70:71], v[58:59]
	v_pk_add_f32 v[48:49], v[48:49], v[50:51]
	v_mul_f32_e32 v47, v16, v16
	v_mul_f32_e32 v72, v17, v17
	v_mul_f32_e32 v73, v18, v18
	v_mul_f32_e32 v74, v19, v19
	v_pk_mov_b32 v[56:57], v[64:65], v[62:63] op_sel:[1,0]
	v_mov_b32_e32 v65, v63
	v_pk_fma_f32 v[62:63], v[20:21], v[20:21], v[2:3] op_sel_hi:[1,1,0]
	v_pk_fma_f32 v[60:61], v[22:23], v[22:23], v[60:61] op_sel_hi:[1,1,0]
	v_pk_add_f32 v[50:51], v[52:53], v[52:53] op_sel:[0,1] op_sel_hi:[1,0]
	v_pk_add_f32 v[48:49], v[48:49], v[48:49] op_sel:[0,1] op_sel_hi:[1,0]
	v_mov_b32_e32 v63, v73
	v_mov_b32_e32 v61, v74
	v_mov_b32_e32 v51, v72
	v_mov_b32_e32 v49, v47
	v_pk_add_f32 v[52:53], v[62:63], v[60:61]
	v_pk_add_f32 v[48:49], v[48:49], v[50:51]
	s_waitcnt vmcnt(0)
	v_mul_f32_e32 v66, v33, v33
	v_mul_f32_e32 v68, v35, v35
	v_pk_add_f32 v[54:55], v[56:57], v[64:65]
	v_pk_add_f32 v[48:49], v[48:49], v[52:53]
	v_mul_f32_e32 v75, v28, v28
	v_mul_f32_e32 v76, v29, v29
	v_mul_f32_e32 v77, v30, v30
	v_mul_f32_e32 v78, v31, v31
	v_pk_fma_f32 v[66:67], v[32:33], v[32:33], v[66:67] op_sel_hi:[1,1,0]
	v_pk_fma_f32 v[68:69], v[34:35], v[34:35], v[68:69] op_sel_hi:[1,1,0]
	v_pk_add_f32 v[54:55], v[54:55], v[54:55] op_sel:[0,1] op_sel_hi:[1,0]
	v_pk_add_f32 v[48:49], v[48:49], v[48:49] op_sel:[0,1] op_sel_hi:[1,0]
	v_mov_b32_e32 v67, v77
	v_mov_b32_e32 v69, v78
	v_mov_b32_e32 v55, v76
	v_mov_b32_e32 v49, v75
	v_pk_add_f32 v[56:57], v[66:67], v[68:69]
	v_pk_add_f32 v[48:49], v[48:49], v[54:55]
	s_nop 0
	v_pk_add_f32 v[48:49], v[48:49], v[56:57]
	s_nop 0
	v_add_f32_e32 v2, v48, v49
	ds_bpermute_b32 v47, v41, v2
	s_waitcnt lgkmcnt(0)
	v_add_f32_e32 v2, v2, v47
	ds_bpermute_b32 v47, v42, v2
	s_waitcnt lgkmcnt(0)
	v_add_f32_e32 v2, v2, v47
	ds_bpermute_b32 v47, v43, v2
	s_waitcnt lgkmcnt(0)
	v_add_f32_e32 v2, v2, v47
	ds_bpermute_b32 v47, v44, v2
	s_waitcnt lgkmcnt(0)
	v_add_f32_e32 v2, v2, v47
	ds_bpermute_b32 v47, v45, v2
	s_waitcnt lgkmcnt(0)
	v_add_f32_e32 v2, v2, v47
	ds_bpermute_b32 v47, v46, v2
	s_waitcnt lgkmcnt(0)
	v_add_f32_e32 v2, v2, v47
	v_fmamk_f32 v2, v2, 0x3a000000, v201
	v_mul_f32_e32 v47, 0x4f800000, v2
	v_cmp_gt_f32_e32 vcc, s91, v2
	s_nop 1
	v_cndmask_b32_e32 v2, v2, v47, vcc
	v_sqrt_f32_e32 v47, v2
	s_nop 0
	v_add_u32_e32 v48, -1, v47
	v_add_u32_e32 v49, 1, v47
	v_fma_f32 v50, -v48, v47, v2
	v_fma_f32 v51, -v49, v47, v2
	v_cmp_ge_f32_e64 s[42:43], 0, v50
	s_nop 1
	v_cndmask_b32_e64 v47, v47, v48, s[42:43]
	v_cmp_lt_f32_e64 s[42:43], 0, v51
	s_nop 1
	v_cndmask_b32_e64 v47, v47, v49, s[42:43]
	v_mul_f32_e32 v48, 0x37800000, v47
	v_cndmask_b32_e32 v47, v47, v48, vcc
	v_cmp_class_f32_e32 vcc, v2, v202
	s_nop 1
	v_cndmask_b32_e32 v2, v47, v2, vcc
	v_div_scale_f32 v47, s[6:7], v2, v2, 1.0
	v_rcp_f32_e32 v49, v47
	v_div_scale_f32 v48, vcc, 1.0, v2, 1.0
	v_fma_f32 v50, -v47, v49, 1.0
	v_fmac_f32_e32 v49, v50, v49
	v_mul_f32_e32 v50, v48, v49
	v_fma_f32 v51, -v47, v50, v48
	v_fmac_f32_e32 v50, v51, v49
	v_fma_f32 v47, -v47, v50, v48
	v_div_fmas_f32 v47, v47, v49, v50
	v_div_fixup_f32 v2, v47, v2, 1.0
	v_pk_mul_f32 v[8:9], v[8:9], v[2:3] op_sel_hi:[1,0]
	v_pk_mul_f32 v[10:11], v[10:11], v[2:3] op_sel_hi:[1,0]
	v_pk_mul_f32 v[4:5], v[4:5], v[2:3] op_sel_hi:[1,0]
	v_pk_mul_f32 v[6:7], v[6:7], v[2:3] op_sel_hi:[1,0]
	v_pk_mul_f32 v[12:13], v[12:13], v[2:3] op_sel_hi:[1,0]
	v_pk_mul_f32 v[14:15], v[14:15], v[2:3] op_sel_hi:[1,0]
	v_pk_mul_f32 v[20:21], v[20:21], v[2:3] op_sel_hi:[1,0]
	v_pk_mul_f32 v[22:23], v[22:23], v[2:3] op_sel_hi:[1,0]
	v_pk_mul_f32 v[16:17], v[16:17], v[2:3] op_sel_hi:[1,0]
	v_pk_mul_f32 v[18:19], v[18:19], v[2:3] op_sel_hi:[1,0]
	v_pk_mul_f32 v[24:25], v[24:25], v[2:3] op_sel_hi:[1,0]
	v_pk_mul_f32 v[26:27], v[26:27], v[2:3] op_sel_hi:[1,0]
	v_pk_mul_f32 v[32:33], v[32:33], v[2:3] op_sel_hi:[1,0]
	v_pk_mul_f32 v[34:35], v[34:35], v[2:3] op_sel_hi:[1,0]
	v_pk_mul_f32 v[28:29], v[28:29], v[2:3] op_sel_hi:[1,0]
	v_pk_mul_f32 v[30:31], v[30:31], v[2:3] op_sel_hi:[1,0]
	v_cvt_pk_bf16_f32 v8, v8, v9
	v_cvt_pk_bf16_f32 v9, v10, v11
	v_cvt_pk_bf16_f32 v4, v4, v5
	v_cvt_pk_bf16_f32 v5, v6, v7
	v_cvt_pk_bf16_f32 v6, v12, v13
	v_cvt_pk_bf16_f32 v7, v14, v15
	v_cvt_pk_bf16_f32 v10, v20, v21
	v_cvt_pk_bf16_f32 v11, v22, v23
	v_cvt_pk_bf16_f32 v12, v16, v17
	v_cvt_pk_bf16_f32 v13, v18, v19
	v_cvt_pk_bf16_f32 v14, v24, v25
	v_cvt_pk_bf16_f32 v15, v26, v27
	v_cvt_pk_bf16_f32 v16, v32, v33
	v_cvt_pk_bf16_f32 v17, v34, v35
	v_cvt_pk_bf16_f32 v18, v28, v29
	v_cvt_pk_bf16_f32 v19, v30, v31
	global_store_dwordx2 v[36:37], v[8:9], off
	global_store_dwordx2 v[36:37], v[4:5], off offset:512
	global_store_dwordx2 v[36:37], v[6:7], off offset:1024
	global_store_dwordx2 v[36:37], v[10:11], off offset:1536
	global_store_dwordx2 v[36:37], v[12:13], off offset:2048
	global_store_dwordx2 v[36:37], v[14:15], off offset:2560
	global_store_dwordx2 v[36:37], v[16:17], off offset:3072
	global_store_dwordx2 v[36:37], v[18:19], off offset:3584
	v_lshl_add_u64 v[36:37], v[36:37], 0, s[20:21]
	s_cbranch_scc1 .LBB0_31

.LBB0_74:
	v_lshl_add_u64 v[8:9], s[44:45], 2, v[78:79]
	global_load_dwordx4 v[4:7], v[8:9], off nt
	s_nop 0
	global_load_dwordx4 v[8:11], v[8:9], off offset:16 nt

.LBB0_92:
	s_lshl_b32 s44, s44, 6
	v_or_b32_e32 v73, s44, v69
	s_cmp_gt_i32 s78, -1
	v_ashrrev_i32_e32 v5, 31, v73
	s_cselect_b64 s[46:47], -1, 0
	s_cmp_lt_i32 s78, 0
	v_lshl_add_u64 v[80:81], s[78:79], 2, v[74:75]
	v_mov_b32_e32 v4, 0
	v_mul_lo_u32 v86, s36, v5
	v_mov_b32_e32 v8, 0
	v_mov_b32_e32 v9, 0
	v_mov_b32_e32 v10, 0
	v_mov_b32_e32 v11, 0
	s_cbranch_scc1 .LBB0_94
	v_mul_lo_u32 v5, s37, v73
	v_mad_u64_u32 v[6:7], s[42:43], s36, v73, 0
	v_add3_u32 v7, v7, v86, v5
	v_lshl_add_u64 v[6:7], v[6:7], 2, v[80:81]
	global_load_dwordx4 v[8:11], v[6:7], off nt
.LBB0_94:
	v_cndmask_b32_e64 v5, 0, 1, s[46:47]
	v_cmp_ne_u32_e64 s[42:43], 1, v5
	s_andn2_b64 vcc, exec, s[46:47]
	v_mov_b32_e32 v5, 0
	v_mov_b32_e32 v6, 0
	v_mov_b32_e32 v7, 0
	s_cbranch_vccnz .LBB0_96
	v_or_b32_e32 v4, 4, v73
	v_mul_lo_u32 v6, s37, v4
	v_mad_u64_u32 v[4:5], s[46:47], s36, v4, 0
	v_add3_u32 v5, v5, v86, v6
	v_lshl_add_u64 v[4:5], v[4:5], 2, v[80:81]
	global_load_dwordx4 v[4:7], v[4:5], off nt
.LBB0_96:
	v_mov_b32_e32 v12, 0
	s_and_b64 vcc, exec, s[42:43]
	v_mov_b32_e32 v16, 0
	v_mov_b32_e32 v17, 0
	v_mov_b32_e32 v18, 0
	v_mov_b32_e32 v19, 0
	s_cbranch_vccnz .LBB0_98
	v_or_b32_e32 v13, 8, v73
	v_mul_lo_u32 v16, s37, v13
	v_mad_u64_u32 v[14:15], s[46:47], s36, v13, 0
	v_add3_u32 v15, v15, v86, v16
	v_lshl_add_u64 v[14:15], v[14:15], 2, v[80:81]
	global_load_dwordx4 v[16:19], v[14:15], off nt
.LBB0_98:
	s_and_b64 vcc, exec, s[42:43]
	v_mov_b32_e32 v13, 0
	v_mov_b32_e32 v14, 0
	v_mov_b32_e32 v15, 0
	s_cbranch_vccnz .LBB0_100
	v_or_b32_e32 v12, 12, v73
	v_mul_lo_u32 v14, s37, v12
	v_mad_u64_u32 v[12:13], s[46:47], s36, v12, 0
	v_add3_u32 v13, v13, v86, v14
	v_lshl_add_u64 v[12:13], v[12:13], 2, v[80:81]
	global_load_dwordx4 v[12:15], v[12:13], off nt
.LBB0_100:
	v_mov_b32_e32 v20, 0
	s_and_b64 vcc, exec, s[42:43]
	v_mov_b32_e32 v24, 0
	v_mov_b32_e32 v25, 0
	v_mov_b32_e32 v26, 0
	v_mov_b32_e32 v27, 0
	s_cbranch_vccnz .LBB0_102
	v_or_b32_e32 v21, 16, v73
	v_mul_lo_u32 v24, s37, v21
	v_mad_u64_u32 v[22:23], s[46:47], s36, v21, 0
	v_add3_u32 v23, v23, v86, v24
	v_lshl_add_u64 v[22:23], v[22:23], 2, v[80:81]
	global_load_dwordx4 v[24:27], v[22:23], off nt
.LBB0_102:
	s_and_b64 vcc, exec, s[42:43]
	v_mov_b32_e32 v21, 0
	v_mov_b32_e32 v22, 0
	v_mov_b32_e32 v23, 0
	s_cbranch_vccnz .LBB0_104
	v_or_b32_e32 v20, 20, v73
	v_mul_lo_u32 v22, s37, v20
	v_mad_u64_u32 v[20:21], s[46:47], s36, v20, 0
	v_add3_u32 v21, v21, v86, v22
	v_lshl_add_u64 v[20:21], v[20:21], 2, v[80:81]
	global_load_dwordx4 v[20:23], v[20:21], off nt
.LBB0_104:
	v_mov_b32_e32 v28, 0
	s_and_b64 vcc, exec, s[42:43]
	v_mov_b32_e32 v32, 0
	v_mov_b32_e32 v33, 0
	v_mov_b32_e32 v34, 0
	v_mov_b32_e32 v35, 0
	s_cbranch_vccnz .LBB0_106
	v_or_b32_e32 v29, 24, v73
	v_mul_lo_u32 v32, s37, v29
	v_mad_u64_u32 v[30:31], s[46:47], s36, v29, 0
	v_add3_u32 v31, v31, v86, v32
	v_lshl_add_u64 v[30:31], v[30:31], 2, v[80:81]
	global_load_dwordx4 v[32:35], v[30:31], off nt
.LBB0_106:
	s_and_b64 vcc, exec, s[42:43]
	v_mov_b32_e32 v29, 0
	v_mov_b32_e32 v30, 0
	v_mov_b32_e32 v31, 0
	s_cbranch_vccnz .LBB0_108
	v_or_b32_e32 v28, 28, v73
	v_mul_lo_u32 v30, s37, v28
	v_mad_u64_u32 v[28:29], s[46:47], s36, v28, 0
	v_add3_u32 v29, v29, v86, v30
	v_lshl_add_u64 v[28:29], v[28:29], 2, v[80:81]
	global_load_dwordx4 v[28:31], v[28:29], off nt
.LBB0_108:
	v_mov_b32_e32 v36, 0
	s_and_b64 vcc, exec, s[42:43]
	v_mov_b32_e32 v40, 0
	v_mov_b32_e32 v41, 0
	v_mov_b32_e32 v42, 0
	v_mov_b32_e32 v43, 0
	s_cbranch_vccnz .LBB0_110
	v_or_b32_e32 v37, 32, v73
	v_mul_lo_u32 v40, s37, v37
	v_mad_u64_u32 v[38:39], s[46:47], s36, v37, 0
	v_add3_u32 v39, v39, v86, v40
	v_lshl_add_u64 v[38:39], v[38:39], 2, v[80:81]
	global_load_dwordx4 v[40:43], v[38:39], off nt
.LBB0_110:
	s_and_b64 vcc, exec, s[42:43]
	v_mov_b32_e32 v37, 0
	v_mov_b32_e32 v38, 0
	v_mov_b32_e32 v39, 0
	s_cbranch_vccnz .LBB0_112
	v_or_b32_e32 v36, 36, v73
	v_mul_lo_u32 v38, s37, v36
	v_mad_u64_u32 v[36:37], s[46:47], s36, v36, 0
	v_add3_u32 v37, v37, v86, v38
	v_lshl_add_u64 v[36:37], v[36:37], 2, v[80:81]
	global_load_dwordx4 v[36:39], v[36:37], off nt
.LBB0_112:
	v_mov_b32_e32 v44, 0
	s_and_b64 vcc, exec, s[42:43]
	v_mov_b32_e32 v48, 0
	v_mov_b32_e32 v49, 0
	v_mov_b32_e32 v50, 0
	v_mov_b32_e32 v51, 0
	s_cbranch_vccnz .LBB0_114
	v_or_b32_e32 v45, 40, v73
	v_mul_lo_u32 v48, s37, v45
	v_mad_u64_u32 v[46:47], s[46:47], s36, v45, 0
	v_add3_u32 v47, v47, v86, v48
	v_lshl_add_u64 v[46:47], v[46:47], 2, v[80:81]
	global_load_dwordx4 v[48:51], v[46:47], off nt
.LBB0_114:
	s_and_b64 vcc, exec, s[42:43]
	v_mov_b32_e32 v45, 0
	v_mov_b32_e32 v46, 0
	v_mov_b32_e32 v47, 0
	s_cbranch_vccnz .LBB0_116
	v_or_b32_e32 v44, 44, v73
	v_mul_lo_u32 v46, s37, v44
	v_mad_u64_u32 v[44:45], s[46:47], s36, v44, 0
	v_add3_u32 v45, v45, v86, v46
	v_lshl_add_u64 v[44:45], v[44:45], 2, v[80:81]
	global_load_dwordx4 v[44:47], v[44:45], off nt
.LBB0_116:
	v_mov_b32_e32 v52, 0
	s_and_b64 vcc, exec, s[42:43]
	v_mov_b32_e32 v56, 0
	v_mov_b32_e32 v57, 0
	v_mov_b32_e32 v58, 0
	v_mov_b32_e32 v59, 0
	s_cbranch_vccnz .LBB0_118
	v_or_b32_e32 v53, 48, v73
	v_mul_lo_u32 v56, s37, v53
	v_mad_u64_u32 v[54:55], s[46:47], s36, v53, 0
	v_add3_u32 v55, v55, v86, v56
	v_lshl_add_u64 v[54:55], v[54:55], 2, v[80:81]
	global_load_dwordx4 v[56:59], v[54:55], off nt
.LBB0_118:
	s_and_b64 vcc, exec, s[42:43]
	v_mov_b32_e32 v53, 0
	v_mov_b32_e32 v54, 0
	v_mov_b32_e32 v55, 0
	s_cbranch_vccnz .LBB0_120
	v_or_b32_e32 v52, 52, v73
	v_mul_lo_u32 v54, s37, v52
	v_mad_u64_u32 v[52:53], s[46:47], s36, v52, 0
	v_add3_u32 v53, v53, v86, v54
	v_lshl_add_u64 v[52:53], v[52:53], 2, v[80:81]
	global_load_dwordx4 v[52:55], v[52:53], off nt
.LBB0_120:
	v_mov_b32_e32 v60, 0
	s_and_b64 vcc, exec, s[42:43]
	v_mov_b32_e32 v64, 0
	v_mov_b32_e32 v65, 0
	v_mov_b32_e32 v66, 0
	v_mov_b32_e32 v67, 0
	s_cbranch_vccnz .LBB0_122
	v_or_b32_e32 v61, 56, v73
	v_mul_lo_u32 v64, s37, v61
	v_mad_u64_u32 v[62:63], s[46:47], s36, v61, 0
	v_add3_u32 v63, v63, v86, v64
	v_lshl_add_u64 v[62:63], v[62:63], 2, v[80:81]
	global_load_dwordx4 v[64:67], v[62:63], off nt
.LBB0_122:
	s_and_b64 vcc, exec, s[42:43]
	v_mov_b32_e32 v61, 0
	v_mov_b32_e32 v62, 0
	v_mov_b32_e32 v63, 0
	s_cbranch_vccnz .LBB0_124
	v_or_b32_e32 v60, 60, v73
	v_mul_lo_u32 v62, s37, v60
	v_mad_u64_u32 v[60:61], s[42:43], s36, v60, 0
	v_add3_u32 v61, v61, v86, v62
	v_lshl_add_u64 v[60:61], v[60:61], 2, v[80:81]
	global_load_dwordx4 v[60:63], v[60:61], off nt

.LBB0_129:
	v_lshlrev_b32_e32 v2, 4, v82
	global_load_dwordx4 v[8:11], v2, s[28:29]
	global_load_dwordx4 v[4:7], v2, s[28:29] offset:1024
	global_load_dwordx4 v[12:15], v2, s[28:29] offset:2048
	global_load_dwordx4 v[16:19], v2, s[28:29] offset:3072
	v_lshl_add_u64 v[20:21], s[28:29], 0, v[2:3]
	s_movk_i32 s7, 0x1000
	v_add_co_u32_e32 v32, vcc, s7, v20
	s_lshl_b64 s[8:9], s[26:27], 12
	s_nop 0
	v_addc_co_u32_e32 v33, vcc, 0, v21, vcc
	global_load_dwordx4 v[20:23], v[32:33], off nt
	global_load_dwordx4 v[24:27], v[32:33], off offset:1024 nt
	global_load_dwordx4 v[28:31], v[32:33], off offset:3072 nt
	s_nop 0
	global_load_dwordx4 v[32:35], v[32:33], off offset:2048 nt
	s_add_u32 s24, s24, s18
	s_addc_u32 s25, s25, s19
	s_add_u32 s20, s20, s22
	s_addc_u32 s21, s21, s23
	s_cmpk_gt_i32 s24, 0x27ff
	s_waitcnt vmcnt(0)
	v_mov_b32_e32 v48, v9
	s_waitcnt vmcnt(6)
	v_mov_b32_e32 v49, v5
	v_mov_b32_e32 v52, v11
	v_mov_b32_e32 v53, v7
	v_mov_b32_e32 v40, v8
	v_mov_b32_e32 v41, v4
	v_mov_b32_e32 v50, v10
	v_mov_b32_e32 v51, v6
	s_waitcnt vmcnt(5)
	v_pk_mul_f32 v[54:55], v[14:15], v[14:15]
	v_pk_mul_f32 v[56:57], v[12:13], v[12:13]
	v_pk_mul_f32 v[48:49], v[48:49], v[48:49]
	v_pk_mul_f32 v[52:53], v[52:53], v[52:53]
	v_pk_mov_b32 v[60:61], v[56:57], v[54:55] op_sel:[1,0]
	v_mov_b32_e32 v57, v55
	v_pk_fma_f32 v[40:41], v[40:41], v[40:41], v[48:49]
	v_pk_fma_f32 v[48:49], v[50:51], v[50:51], v[52:53]
	s_waitcnt vmcnt(4)
	v_mul_f32_e32 v2, v17, v17
	v_mul_f32_e32 v58, v19, v19
	v_pk_add_f32 v[50:51], v[60:61], v[56:57]
	v_pk_add_f32 v[40:41], v[40:41], v[48:49]
	v_pk_fma_f32 v[54:55], v[16:17], v[16:17], v[2:3] op_sel_hi:[1,1,0]
	v_pk_fma_f32 v[58:59], v[18:19], v[18:19], v[58:59] op_sel_hi:[1,1,0]
	s_waitcnt vmcnt(3)
	v_mul_f32_e32 v47, v20, v20
	v_mul_f32_e32 v62, v21, v21
	v_pk_add_f32 v[48:49], v[50:51], v[50:51] op_sel:[0,1] op_sel_hi:[1,0]
	v_pk_add_f32 v[40:41], v[40:41], v[40:41] op_sel:[0,1] op_sel_hi:[1,0]
	v_mul_f32_e32 v55, v22, v22
	v_mul_f32_e32 v59, v23, v23
	s_waitcnt vmcnt(2)
	v_pk_mul_f32 v[52:53], v[26:27], v[26:27]
	v_pk_mul_f32 v[56:57], v[24:25], v[24:25]
	v_mov_b32_e32 v49, v62
	v_mov_b32_e32 v41, v47
	v_pk_mov_b32 v[50:51], v[56:57], v[52:53] op_sel:[1,0]
	v_mov_b32_e32 v57, v53
	v_pk_add_f32 v[54:55], v[54:55], v[58:59]
	v_pk_add_f32 v[40:41], v[40:41], v[48:49]
	s_waitcnt vmcnt(0)
	v_mul_f32_e32 v2, v33, v33
	v_mul_f32_e32 v60, v35, v35
	v_pk_add_f32 v[50:51], v[50:51], v[56:57]
	v_pk_add_f32 v[40:41], v[40:41], v[54:55]
	v_mul_f32_e32 v63, v28, v28
	v_mul_f32_e32 v64, v29, v29
	v_mul_f32_e32 v65, v30, v30
	v_mul_f32_e32 v66, v31, v31
	v_pk_fma_f32 v[52:53], v[32:33], v[32:33], v[2:3] op_sel_hi:[1,1,0]
	v_pk_fma_f32 v[60:61], v[34:35], v[34:35], v[60:61] op_sel_hi:[1,1,0]
	v_pk_add_f32 v[50:51], v[50:51], v[50:51] op_sel:[0,1] op_sel_hi:[1,0]
	v_pk_add_f32 v[40:41], v[40:41], v[40:41] op_sel:[0,1] op_sel_hi:[1,0]
	v_mov_b32_e32 v53, v65
	v_mov_b32_e32 v61, v66
	v_mov_b32_e32 v51, v64
	v_mov_b32_e32 v41, v63
	v_pk_add_f32 v[52:53], v[52:53], v[60:61]
	v_pk_add_f32 v[40:41], v[40:41], v[50:51]
	s_nop 0
	v_pk_add_f32 v[40:41], v[40:41], v[52:53]
	s_nop 0
	v_add_f32_e32 v2, v40, v41
	ds_bpermute_b32 v40, v37, v2
	s_waitcnt lgkmcnt(0)
	v_add_f32_e32 v2, v2, v40
	ds_bpermute_b32 v40, v42, v2
	s_waitcnt lgkmcnt(0)
	v_add_f32_e32 v2, v2, v40
	ds_bpermute_b32 v40, v43, v2
	s_waitcnt lgkmcnt(0)
	v_add_f32_e32 v2, v2, v40
	ds_bpermute_b32 v40, v44, v2
	s_waitcnt lgkmcnt(0)
	v_add_f32_e32 v2, v2, v40
	ds_bpermute_b32 v40, v45, v2
	s_waitcnt lgkmcnt(0)
	v_add_f32_e32 v2, v2, v40
	ds_bpermute_b32 v47, v46, v2
	v_lshl_add_u64 v[40:41], v[38:39], 0, s[8:9]
	s_waitcnt lgkmcnt(0)
	v_add_f32_e32 v2, v2, v47
	v_fmamk_f32 v2, v2, 0x3a000000, v201
	v_mul_f32_e32 v47, 0x4f800000, v2
	v_cmp_gt_f32_e32 vcc, s91, v2
	s_nop 1
	v_cndmask_b32_e32 v2, v2, v47, vcc
	v_sqrt_f32_e32 v47, v2
	s_nop 0
	v_add_u32_e32 v48, -1, v47
	v_add_u32_e32 v49, 1, v47
	v_fma_f32 v50, -v48, v47, v2
	v_fma_f32 v51, -v49, v47, v2
	v_cmp_ge_f32_e64 s[42:43], 0, v50
	s_nop 1
	v_cndmask_b32_e64 v47, v47, v48, s[42:43]
	v_cmp_lt_f32_e64 s[42:43], 0, v51
	s_nop 1
	v_cndmask_b32_e64 v47, v47, v49, s[42:43]
	v_mul_f32_e32 v48, 0x37800000, v47
	v_cndmask_b32_e32 v47, v47, v48, vcc
	v_cmp_class_f32_e32 vcc, v2, v202
	s_nop 1
	v_cndmask_b32_e32 v2, v47, v2, vcc
	v_div_scale_f32 v47, s[8:9], v2, v2, 1.0
	v_rcp_f32_e32 v48, v47
	v_div_scale_f32 v49, vcc, 1.0, v2, 1.0
	v_fma_f32 v50, -v47, v48, 1.0
	v_fmac_f32_e32 v48, v50, v48
	v_mul_f32_e32 v50, v49, v48
	v_fma_f32 v51, -v47, v50, v49
	v_fmac_f32_e32 v50, v51, v48
	v_fma_f32 v47, -v47, v50, v49
	v_div_fmas_f32 v47, v47, v48, v50
	v_div_fixup_f32 v2, v47, v2, 1.0
	v_pk_mul_f32 v[8:9], v[8:9], v[2:3] op_sel_hi:[1,0]
	v_pk_mul_f32 v[10:11], v[10:11], v[2:3] op_sel_hi:[1,0]
	v_pk_mul_f32 v[18:19], v[18:19], v[2:3] op_sel_hi:[1,0]
	v_pk_mul_f32 v[28:29], v[28:29], v[2:3] op_sel_hi:[1,0]
	v_pk_mul_f32 v[30:31], v[30:31], v[2:3] op_sel_hi:[1,0]
	v_pk_mul_f32 v[4:5], v[4:5], v[2:3] op_sel_hi:[1,0]
	v_pk_mul_f32 v[6:7], v[6:7], v[2:3] op_sel_hi:[1,0]
	v_pk_mul_f32 v[12:13], v[12:13], v[2:3] op_sel_hi:[1,0]
	v_pk_mul_f32 v[14:15], v[14:15], v[2:3] op_sel_hi:[1,0]
	v_pk_mul_f32 v[16:17], v[16:17], v[2:3] op_sel_hi:[1,0]
	v_pk_mul_f32 v[20:21], v[20:21], v[2:3] op_sel_hi:[1,0]
	v_pk_mul_f32 v[22:23], v[22:23], v[2:3] op_sel_hi:[1,0]
	v_pk_mul_f32 v[24:25], v[24:25], v[2:3] op_sel_hi:[1,0]
	v_pk_mul_f32 v[26:27], v[26:27], v[2:3] op_sel_hi:[1,0]
	v_pk_mul_f32 v[32:33], v[32:33], v[2:3] op_sel_hi:[1,0]
	v_pk_mul_f32 v[34:35], v[34:35], v[2:3] op_sel_hi:[1,0]
	v_cvt_pk_bf16_f32 v8, v8, v9
	v_cvt_pk_bf16_f32 v9, v10, v11
	v_cvt_pk_bf16_f32 v11, v18, v19
	v_cvt_pk_bf16_f32 v18, v28, v29
	v_cvt_pk_bf16_f32 v19, v30, v31
	v_cvt_pk_bf16_f32 v4, v4, v5
	v_cvt_pk_bf16_f32 v5, v6, v7
	v_cvt_pk_bf16_f32 v6, v12, v13
	v_cvt_pk_bf16_f32 v7, v14, v15
	v_cvt_pk_bf16_f32 v10, v16, v17
	v_cvt_pk_bf16_f32 v12, v20, v21
	v_cvt_pk_bf16_f32 v13, v22, v23
	v_cvt_pk_bf16_f32 v14, v24, v25
	v_cvt_pk_bf16_f32 v15, v26, v27
	v_cvt_pk_bf16_f32 v16, v32, v33
	v_cvt_pk_bf16_f32 v17, v34, v35
	global_store_dwordx2 v[40:41], v[8:9], off
	global_store_dwordx2 v[40:41], v[4:5], off offset:512
	global_store_dwordx2 v[40:41], v[6:7], off offset:1024
	global_store_dwordx2 v[40:41], v[10:11], off offset:1536
	global_store_dwordx2 v[40:41], v[12:13], off offset:2048
	global_store_dwordx2 v[40:41], v[14:15], off offset:2560
	global_store_dwordx2 v[40:41], v[16:17], off offset:3072
	global_store_dwordx2 v[40:41], v[18:19], off offset:3584
	s_cbranch_scc1 .LBB0_137

.LBB0_139:
	global_load_dwordx4 v[32:35], v[38:39], off offset:-4096 nt
	global_load_dwordx4 v[28:31], v[38:39], off offset:-3072 nt
	global_load_dwordx4 v[24:27], v[38:39], off offset:-2048 nt
	global_load_dwordx4 v[20:23], v[38:39], off offset:-1024 nt
	global_load_dwordx4 v[16:19], v[38:39], off nt
	global_load_dwordx4 v[12:15], v[38:39], off offset:1024 nt
	global_load_dwordx4 v[8:11], v[38:39], off offset:2048 nt
	global_load_dwordx4 v[4:7], v[38:39], off offset:3072 nt
	s_add_i32 s5, s5, s18
	v_lshl_add_u64 v[38:39], v[38:39], 0, s[22:23]
	s_cmp_gt_i32 s5, 0x1ffff
	s_waitcnt vmcnt(0)
	v_mov_b32_e32 v48, v33
	s_waitcnt vmcnt(6)
	v_mov_b32_e32 v49, v29
	v_mov_b32_e32 v52, v35
	v_mov_b32_e32 v53, v31
	v_mov_b32_e32 v46, v32
	v_mov_b32_e32 v47, v28
	v_mov_b32_e32 v50, v34
	v_mov_b32_e32 v51, v30
	s_waitcnt vmcnt(5)
	v_mov_b32_e32 v56, v25
	s_waitcnt vmcnt(4)
	v_mov_b32_e32 v57, v21
	v_mov_b32_e32 v60, v27
	v_mov_b32_e32 v61, v23
	v_pk_mul_f32 v[48:49], v[48:49], v[48:49]
	v_pk_mul_f32 v[52:53], v[52:53], v[52:53]
	v_mov_b32_e32 v54, v24
	v_mov_b32_e32 v55, v20
	v_mov_b32_e32 v58, v26
	v_mov_b32_e32 v59, v22
	s_waitcnt vmcnt(3)
	v_mov_b32_e32 v64, v17
	s_waitcnt vmcnt(2)
	v_mov_b32_e32 v65, v13
	v_mov_b32_e32 v70, v19
	v_mov_b32_e32 v71, v15
	v_pk_mul_f32 v[56:57], v[56:57], v[56:57]
	v_pk_mul_f32 v[60:61], v[60:61], v[60:61]
	v_pk_fma_f32 v[46:47], v[46:47], v[46:47], v[48:49]
	v_pk_fma_f32 v[48:49], v[50:51], v[50:51], v[52:53]
	v_mov_b32_e32 v62, v16
	v_mov_b32_e32 v63, v12
	v_mov_b32_e32 v66, v18
	v_mov_b32_e32 v67, v14
	s_waitcnt vmcnt(1)
	v_mov_b32_e32 v74, v9
	s_waitcnt vmcnt(0)
	v_mov_b32_e32 v75, v5
	v_mov_b32_e32 v78, v11
	v_mov_b32_e32 v79, v7
	v_pk_mul_f32 v[64:65], v[64:65], v[64:65]
	v_pk_mul_f32 v[70:71], v[70:71], v[70:71]
	v_pk_fma_f32 v[50:51], v[54:55], v[54:55], v[56:57]
	v_pk_fma_f32 v[52:53], v[58:59], v[58:59], v[60:61]
	v_pk_add_f32 v[46:47], v[46:47], v[48:49]
	v_mov_b32_e32 v72, v8
	v_mov_b32_e32 v73, v4
	v_mov_b32_e32 v76, v10
	v_mov_b32_e32 v77, v6
	v_pk_mul_f32 v[74:75], v[74:75], v[74:75]
	v_pk_mul_f32 v[78:79], v[78:79], v[78:79]
	v_pk_fma_f32 v[54:55], v[62:63], v[62:63], v[64:65]
	v_pk_fma_f32 v[56:57], v[66:67], v[66:67], v[70:71]
	v_pk_add_f32 v[48:49], v[50:51], v[52:53]
	v_add_f32_e32 v2, v46, v47
	v_pk_fma_f32 v[58:59], v[72:73], v[72:73], v[74:75]
	v_pk_fma_f32 v[60:61], v[76:77], v[76:77], v[78:79]
	v_pk_add_f32 v[50:51], v[54:55], v[56:57]
	v_add_f32_e32 v46, v48, v49
	ds_bpermute_b32 v49, v40, v2
	v_pk_add_f32 v[52:53], v[58:59], v[60:61]
	v_add_f32_e32 v47, v50, v51
	ds_bpermute_b32 v50, v40, v46
	v_add_f32_e32 v48, v52, v53
	ds_bpermute_b32 v51, v40, v47
	ds_bpermute_b32 v52, v40, v48
	s_waitcnt lgkmcnt(3)
	v_add_f32_e32 v2, v2, v49
	s_waitcnt lgkmcnt(2)
	v_add_f32_e32 v46, v46, v50
	ds_bpermute_b32 v49, v41, v2
	s_waitcnt lgkmcnt(2)
	v_add_f32_e32 v47, v47, v51
	ds_bpermute_b32 v50, v41, v46
	s_waitcnt lgkmcnt(2)
	v_add_f32_e32 v48, v48, v52
	ds_bpermute_b32 v51, v41, v47
	ds_bpermute_b32 v52, v41, v48
	s_waitcnt lgkmcnt(3)
	v_add_f32_e32 v2, v2, v49
	s_waitcnt lgkmcnt(2)
	v_add_f32_e32 v46, v46, v50
	ds_bpermute_b32 v49, v42, v2
	s_waitcnt lgkmcnt(2)
	v_add_f32_e32 v47, v47, v51
	ds_bpermute_b32 v50, v42, v46
	s_waitcnt lgkmcnt(2)
	v_add_f32_e32 v48, v48, v52
	ds_bpermute_b32 v51, v42, v47
	ds_bpermute_b32 v52, v42, v48
	s_waitcnt lgkmcnt(3)
	v_add_f32_e32 v2, v2, v49
	s_waitcnt lgkmcnt(2)
	v_add_f32_e32 v46, v46, v50
	ds_bpermute_b32 v49, v43, v2
	s_waitcnt lgkmcnt(2)
	v_add_f32_e32 v47, v47, v51
	ds_bpermute_b32 v50, v43, v46
	s_waitcnt lgkmcnt(2)
	v_add_f32_e32 v48, v48, v52
	ds_bpermute_b32 v51, v43, v47
	ds_bpermute_b32 v52, v43, v48
	s_waitcnt lgkmcnt(3)
	v_add_f32_e32 v2, v2, v49
	s_waitcnt lgkmcnt(2)
	v_add_f32_e32 v46, v46, v50
	ds_bpermute_b32 v49, v44, v2
	s_waitcnt lgkmcnt(2)
	v_add_f32_e32 v47, v47, v51
	ds_bpermute_b32 v50, v44, v46
	s_waitcnt lgkmcnt(2)
	v_add_f32_e32 v48, v48, v52
	ds_bpermute_b32 v51, v44, v47
	ds_bpermute_b32 v52, v44, v48
	s_waitcnt lgkmcnt(3)
	v_add_f32_e32 v2, v2, v49
	s_waitcnt lgkmcnt(2)
	v_add_f32_e32 v46, v46, v50
	ds_bpermute_b32 v49, v45, v2
	s_waitcnt lgkmcnt(2)
	v_add_f32_e32 v47, v47, v51
	ds_bpermute_b32 v50, v45, v46
	s_waitcnt lgkmcnt(2)
	v_add_f32_e32 v48, v48, v52
	ds_bpermute_b32 v51, v45, v47
	ds_bpermute_b32 v52, v45, v48
	s_waitcnt lgkmcnt(3)
	v_add_f32_e32 v2, v2, v49
	s_waitcnt lgkmcnt(2)
	v_add_f32_e32 v46, v46, v50
	v_fmamk_f32 v2, v2, 0x3b000000, v201
	s_waitcnt lgkmcnt(1)
	v_add_f32_e32 v47, v47, v51
	v_fmamk_f32 v46, v46, 0x3b000000, v201
	v_mul_f32_e32 v49, 0x4f800000, v2
	v_cmp_gt_f32_e64 s[46:47], s91, v2
	s_waitcnt lgkmcnt(0)
	v_add_f32_e32 v48, v48, v52
	v_fmamk_f32 v47, v47, 0x3b000000, v201
	v_mul_f32_e32 v50, 0x4f800000, v46
	v_cmp_gt_f32_e32 vcc, s91, v46
	v_cndmask_b32_e64 v2, v2, v49, s[46:47]
	v_fmamk_f32 v48, v48, 0x3b000000, v201
	v_mul_f32_e32 v51, 0x4f800000, v47
	v_cmp_gt_f32_e64 s[42:43], s91, v47
	v_cndmask_b32_e32 v46, v46, v50, vcc
	v_sqrt_f32_e32 v49, v2
	v_mul_f32_e32 v52, 0x4f800000, v48
	v_cmp_gt_f32_e64 s[44:45], s91, v48
	v_cndmask_b32_e64 v47, v47, v51, s[42:43]
	v_sqrt_f32_e32 v50, v46
	v_cndmask_b32_e64 v48, v48, v52, s[44:45]
	v_sqrt_f32_e32 v51, v47
	v_sqrt_f32_e32 v52, v48
	v_add_u32_e32 v53, -1, v49
	v_add_u32_e32 v54, 1, v49
	v_add_u32_e32 v55, -1, v50
	v_fma_f32 v61, -v53, v49, v2
	v_add_u32_e32 v56, 1, v50
	v_add_u32_e32 v57, -1, v51
	v_fma_f32 v62, -v54, v49, v2
	v_fma_f32 v63, -v55, v50, v46
	v_cmp_ge_f32_e64 s[48:49], 0, v61
	v_add_u32_e32 v58, 1, v51
	v_add_u32_e32 v59, -1, v52
	v_fma_f32 v64, -v56, v50, v46
	v_fma_f32 v65, -v57, v51, v47
	v_cndmask_b32_e64 v49, v49, v53, s[48:49]
	v_cmp_ge_f32_e64 s[48:49], 0, v63
	v_cmp_lt_f32_e64 s[54:55], 0, v62
	v_add_u32_e32 v60, 1, v52
	v_fma_f32 v66, -v58, v51, v47
	v_fma_f32 v67, -v59, v52, v48
	v_cndmask_b32_e64 v50, v50, v55, s[48:49]
	v_cmp_lt_f32_e64 s[48:49], 0, v64
	v_cmp_ge_f32_e64 s[50:51], 0, v65
	v_cndmask_b32_e64 v49, v49, v54, s[54:55]
	v_fma_f32 v69, -v60, v52, v48
	v_cndmask_b32_e64 v51, v51, v57, s[50:51]
	v_cmp_lt_f32_e64 s[50:51], 0, v66
	v_cmp_ge_f32_e64 s[52:53], 0, v67
	v_cndmask_b32_e64 v50, v50, v56, s[48:49]
	v_mul_f32_e32 v53, 0x37800000, v49
	v_cndmask_b32_e64 v52, v52, v59, s[52:53]
	v_cmp_lt_f32_e64 s[52:53], 0, v69
	v_cndmask_b32_e64 v51, v51, v58, s[50:51]
	v_mul_f32_e32 v54, 0x37800000, v50
	v_cndmask_b32_e64 v49, v49, v53, s[46:47]
	v_cmp_class_f32_e64 s[46:47], v2, v202
	v_cndmask_b32_e64 v52, v52, v60, s[52:53]
	v_mul_f32_e32 v55, 0x37800000, v51
	v_cndmask_b32_e32 v50, v50, v54, vcc
	v_cmp_class_f32_e32 vcc, v46, v202
	v_cndmask_b32_e64 v2, v49, v2, s[46:47]
	v_mul_f32_e32 v56, 0x37800000, v52
	v_cndmask_b32_e64 v51, v51, v55, s[42:43]
	v_cmp_class_f32_e64 s[42:43], v47, v202
	v_cndmask_b32_e32 v46, v50, v46, vcc
	v_div_scale_f32 v49, s[6:7], v2, v2, 1.0
	v_cndmask_b32_e64 v52, v52, v56, s[44:45]
	v_cmp_class_f32_e64 s[44:45], v48, v202
	v_cndmask_b32_e64 v47, v51, v47, s[42:43]
	v_div_scale_f32 v51, s[6:7], v46, v46, 1.0
	v_rcp_f32_e32 v57, v49
	v_cndmask_b32_e64 v48, v52, v48, s[44:45]
	v_div_scale_f32 v53, s[6:7], v47, v47, 1.0
	v_rcp_f32_e32 v58, v51
	v_div_scale_f32 v55, s[6:7], v48, v48, 1.0
	v_rcp_f32_e32 v59, v53
	v_rcp_f32_e32 v60, v55
	v_fma_f32 v61, -v49, v57, 1.0
	v_div_scale_f32 v50, vcc, 1.0, v2, 1.0
	v_fma_f32 v62, -v51, v58, 1.0
	v_fmac_f32_e32 v57, v61, v57
	v_div_scale_f32 v52, s[42:43], 1.0, v46, 1.0
	v_fma_f32 v63, -v53, v59, 1.0
	v_fmac_f32_e32 v58, v62, v58
	v_mul_f32_e32 v61, v50, v57
	v_div_scale_f32 v54, s[44:45], 1.0, v47, 1.0
	v_fma_f32 v64, -v55, v60, 1.0
	v_fmac_f32_e32 v59, v63, v59
	v_mul_f32_e32 v62, v52, v58
	v_fma_f32 v65, -v49, v61, v50
	v_div_scale_f32 v56, s[46:47], 1.0, v48, 1.0
	v_fmac_f32_e32 v60, v64, v60
	v_mul_f32_e32 v63, v54, v59
	v_fma_f32 v66, -v51, v62, v52
	v_fmac_f32_e32 v61, v65, v57
	v_mul_f32_e32 v64, v56, v60
	v_fma_f32 v67, -v53, v63, v54
	v_fmac_f32_e32 v62, v66, v58
	v_fma_f32 v49, -v49, v61, v50
	v_fma_f32 v69, -v55, v64, v56
	v_fmac_f32_e32 v63, v67, v59
	v_fma_f32 v50, -v51, v62, v52
	v_div_fmas_f32 v49, v49, v57, v61
	s_mov_b64 vcc, s[42:43]
	v_fmac_f32_e32 v64, v69, v60
	v_fma_f32 v51, -v53, v63, v54
	v_div_fixup_f32 v2, v49, v2, 1.0
	v_div_fmas_f32 v49, v50, v58, v62
	s_mov_b64 vcc, s[44:45]
	v_fma_f32 v52, -v55, v64, v56
	v_pk_mul_f32 v[32:33], v[32:33], v[2:3] op_sel_hi:[1,0]
	v_pk_mul_f32 v[34:35], v[34:35], v[2:3] op_sel_hi:[1,0]
	v_pk_mul_f32 v[28:29], v[28:29], v[2:3] op_sel_hi:[1,0]
	v_pk_mul_f32 v[30:31], v[30:31], v[2:3] op_sel_hi:[1,0]
	v_div_fixup_f32 v2, v49, v46, 1.0
	v_div_fmas_f32 v46, v51, v59, v63
	s_mov_b64 vcc, s[46:47]
	v_cvt_pk_bf16_f32 v28, v28, v29
	v_cvt_pk_bf16_f32 v29, v30, v31
	v_pk_mul_f32 v[24:25], v[24:25], v[2:3] op_sel_hi:[1,0]
	v_pk_mul_f32 v[26:27], v[26:27], v[2:3] op_sel_hi:[1,0]
	v_pk_mul_f32 v[20:21], v[20:21], v[2:3] op_sel_hi:[1,0]
	v_pk_mul_f32 v[22:23], v[22:23], v[2:3] op_sel_hi:[1,0]
	v_div_fixup_f32 v2, v46, v47, 1.0
	v_div_fmas_f32 v30, v52, v60, v64
	v_pk_mul_f32 v[16:17], v[16:17], v[2:3] op_sel_hi:[1,0]
	v_pk_mul_f32 v[18:19], v[18:19], v[2:3] op_sel_hi:[1,0]
	v_pk_mul_f32 v[12:13], v[12:13], v[2:3] op_sel_hi:[1,0]
	v_pk_mul_f32 v[14:15], v[14:15], v[2:3] op_sel_hi:[1,0]
	v_div_fixup_f32 v2, v30, v48, 1.0
	v_pk_mul_f32 v[8:9], v[8:9], v[2:3] op_sel_hi:[1,0]
	v_pk_mul_f32 v[10:11], v[10:11], v[2:3] op_sel_hi:[1,0]
	v_cvt_pk_bf16_f32 v32, v32, v33
	v_cvt_pk_bf16_f32 v33, v34, v35
	v_cvt_pk_bf16_f32 v24, v24, v25
	v_cvt_pk_bf16_f32 v25, v26, v27
	v_cvt_pk_bf16_f32 v16, v16, v17
	v_cvt_pk_bf16_f32 v17, v18, v19
	v_pk_mul_f32 v[4:5], v[4:5], v[2:3] op_sel_hi:[1,0]
	v_pk_mul_f32 v[6:7], v[6:7], v[2:3] op_sel_hi:[1,0]
	v_cvt_pk_bf16_f32 v8, v8, v9
	v_cvt_pk_bf16_f32 v9, v10, v11
	global_store_dwordx2 v[36:37], v[32:33], off
	global_store_dwordx2 v[36:37], v[28:29], off offset:512
	v_cvt_pk_bf16_f32 v20, v20, v21
	v_cvt_pk_bf16_f32 v21, v22, v23
	global_store_dwordx2 v[36:37], v[24:25], off offset:1024
	global_store_dwordx2 v[36:37], v[20:21], off offset:1536
	v_cvt_pk_bf16_f32 v12, v12, v13
	v_cvt_pk_bf16_f32 v13, v14, v15
	global_store_dwordx2 v[36:37], v[16:17], off offset:2048
	global_store_dwordx2 v[36:37], v[12:13], off offset:2560
	v_cvt_pk_bf16_f32 v4, v4, v5
	v_cvt_pk_bf16_f32 v5, v6, v7
	global_store_dwordx2 v[36:37], v[8:9], off offset:3072
	global_store_dwordx2 v[36:37], v[4:5], off offset:3584
	v_lshl_add_u64 v[36:37], v[36:37], 0, s[16:17]
	s_cbranch_scc0 .LBB0_139
